# cross-tile pipelined prompt loop, staging writes and their two barriers right after the last PV MFMA (b1=7)
# speedup vs baseline: 1.0076x; 1.0014x over previous
.LBB0_822:
	s_mov_b32 s5, 0
	v_exp_f32_e32 v124, v84
	v_exp_f32_e32 v125, v85
	v_exp_f32_e32 v126, v86
	v_add_f32_e32 v224, v124, v125
	s_waitcnt lgkmcnt(4)
	v_mfma_f32_32x32x16_bf16 v[4:19], v[164:167], v[144:147], v[4:19]
	v_exp_f32_e32 v127, v87
	v_cvt_pk_bf16_f32 v184, v124, v125
	v_mov_b32_e32 v254, v224
	v_exp_f32_e32 v128, v88
	s_waitcnt lgkmcnt(2)
	v_mfma_f32_32x32x16_bf16 v[20:35], v[168:171], v[144:147], v[20:35]
	ds_read_b64_tr_b16 v[176:177], v162 offset:29760
	ds_read_b64_tr_b16 v[178:179], v162 offset:31296
	v_add_f32_e32 v226, v126, v127
	v_exp_f32_e32 v129, v89
	v_cvt_pk_bf16_f32 v185, v126, v127
	v_add_f32_e32 v254, v254, v226
	s_waitcnt lgkmcnt(2)
	v_mfma_f32_32x32x16_bf16 v[4:19], v[172:175], v[140:143], v[4:19]
	ds_read_b64_tr_b16 v[164:165], v162 offset:32768
	ds_read_b64_tr_b16 v[166:167], v162 offset:34304
	v_exp_f32_e32 v130, v90
	v_add_f32_e32 v233, v128, v129
	v_exp_f32_e32 v131, v91
	v_cvt_pk_bf16_f32 v186, v128, v129
	s_waitcnt lgkmcnt(2)
	v_mfma_f32_32x32x16_bf16 v[20:35], v[176:179], v[140:143], v[20:35]
	ds_read_b64_tr_b16 v[168:169], v162 offset:32832
	ds_read_b64_tr_b16 v[170:171], v162 offset:34368
	v_add_f32_e32 v254, v254, v233
	v_exp_f32_e32 v124, v92
	v_add_f32_e32 v224, v130, v131
	v_exp_f32_e32 v125, v93
	s_waitcnt lgkmcnt(2)
	v_mfma_f32_32x32x16_bf16 v[4:19], v[164:167], v[136:139], v[4:19]
	ds_read_b64_tr_b16 v[172:173], v162 offset:35840
	ds_read_b64_tr_b16 v[174:175], v162 offset:37376
	v_cvt_pk_bf16_f32 v187, v130, v131
	v_add_f32_e32 v254, v254, v224
	v_exp_f32_e32 v126, v94
	v_add_f32_e32 v226, v124, v125
	s_waitcnt lgkmcnt(2)
	v_mfma_f32_32x32x16_bf16 v[20:35], v[168:171], v[136:139], v[20:35]
	ds_read_b64_tr_b16 v[176:177], v162 offset:35904
	ds_read_b64_tr_b16 v[178:179], v162 offset:37440
	v_exp_f32_e32 v127, v95
	v_cvt_pk_bf16_f32 v188, v124, v125
	v_add_f32_e32 v254, v254, v226
	v_exp_f32_e32 v128, v96
	s_waitcnt lgkmcnt(2)
	v_mfma_f32_32x32x16_bf16 v[4:19], v[172:175], v[132:135], v[4:19]
	ds_read_b128 v[180:183], v155 offset:0
	ds_read_b128 v[112:115], v155 offset:6656
	v_add_f32_e32 v233, v126, v127
	v_exp_f32_e32 v129, v97
	v_cvt_pk_bf16_f32 v189, v126, v127
	v_add_f32_e32 v254, v254, v233
	s_waitcnt lgkmcnt(2)
	v_mfma_f32_32x32x16_bf16 v[20:35], v[176:179], v[132:135], v[20:35]
	s_barrier
	s_waitcnt vmcnt(0)
	ds_write_b128 v157, v[104:107] offset:13312
	ds_write_b64 v158, v[108:109] offset:13440
	ds_write_b128 v151, v[100:103] offset:38912
	buffer_load_dwordx2 v[108:109], v161, s[12:15], s52 offen
	s_add_i32 s3, s53, 0xfe040000
	buffer_load_dwordx4 v[104:107], v150, s[12:15], s3 offen
	buffer_load_dwordx4 v[100:103], v150, s[12:15], s53 offen
	ds_read_b128 v[116:119], v155 offset:32
	ds_read_b128 v[120:123], v155 offset:6688
	v_exp_f32_e32 v130, v98
	v_add_f32_e32 v224, v128, v129
	v_exp_f32_e32 v131, v99
	v_cvt_pk_bf16_f32 v190, v128, v129
	s_waitcnt lgkmcnt(6)
	v_mfma_f32_32x32x16_bf16 v[52:67], v[180:183], v[200:203], v[234:249]
	ds_read_b128 v[180:183], v155 offset:64
	v_add_f32_e32 v254, v254, v224
	v_exp_f32_e32 v124, v36
	v_add_f32_e32 v226, v130, v131
	v_exp_f32_e32 v125, v37
	s_waitcnt lgkmcnt(6)
	v_mfma_f32_32x32x16_bf16 v[68:83], v[112:115], v[200:203], v[234:249]
	ds_read_b128 v[112:115], v155 offset:6720
	v_cvt_pk_bf16_f32 v191, v130, v131
	v_add_f32_e32 v254, v254, v226
	v_exp_f32_e32 v126, v38
	v_add_f32_e32 v233, v124, v125
	s_waitcnt lgkmcnt(3)
	v_mfma_f32_32x32x16_bf16 v[52:67], v[116:119], v[204:207], v[52:67]
	s_barrier
	ds_read_b128 v[116:119], v155 offset:96
	v_exp_f32_e32 v127, v39
	v_cvt_pk_bf16_f32 v192, v124, v125
	v_add_f32_e32 v254, v254, v233
	v_exp_f32_e32 v128, v40
	s_waitcnt lgkmcnt(3)
	v_mfma_f32_32x32x16_bf16 v[68:83], v[120:123], v[204:207], v[68:83]
	ds_read_b128 v[120:123], v155 offset:6752
	v_add_f32_e32 v224, v126, v127
	v_exp_f32_e32 v129, v41
	v_cvt_pk_bf16_f32 v193, v126, v127
	v_add_f32_e32 v254, v254, v224
	s_waitcnt lgkmcnt(3)
	v_mfma_f32_32x32x16_bf16 v[52:67], v[180:183], v[208:211], v[52:67]
	ds_read_b128 v[180:183], v155 offset:128
	v_exp_f32_e32 v130, v42
	v_add_f32_e32 v226, v128, v129
	v_exp_f32_e32 v131, v43
	v_cvt_pk_bf16_f32 v194, v128, v129
	s_waitcnt lgkmcnt(3)
	v_mfma_f32_32x32x16_bf16 v[68:83], v[112:115], v[208:211], v[68:83]
	ds_read_b128 v[112:115], v155 offset:6784
	v_add_f32_e32 v254, v254, v226
	v_exp_f32_e32 v124, v44
	v_add_f32_e32 v233, v130, v131
	v_exp_f32_e32 v125, v45
	s_waitcnt lgkmcnt(3)
	v_mfma_f32_32x32x16_bf16 v[52:67], v[116:119], v[212:215], v[52:67]
	ds_read_b128 v[116:119], v155 offset:160
	v_cvt_pk_bf16_f32 v195, v130, v131
	v_add_f32_e32 v254, v254, v233
	v_exp_f32_e32 v126, v46
	v_add_f32_e32 v224, v124, v125
	s_waitcnt lgkmcnt(3)
	v_mfma_f32_32x32x16_bf16 v[68:83], v[120:123], v[212:215], v[68:83]
	ds_read_b128 v[120:123], v155 offset:6816
	v_exp_f32_e32 v127, v47
	v_cvt_pk_bf16_f32 v196, v124, v125
	v_add_f32_e32 v254, v254, v224
	v_exp_f32_e32 v128, v48
	s_waitcnt lgkmcnt(3)
	v_mfma_f32_32x32x16_bf16 v[52:67], v[180:183], v[216:219], v[52:67]
	v_add_f32_e32 v226, v126, v127
	v_exp_f32_e32 v129, v49
	v_cvt_pk_bf16_f32 v197, v126, v127
	v_add_f32_e32 v254, v254, v226
	s_waitcnt lgkmcnt(2)
	v_mfma_f32_32x32x16_bf16 v[68:83], v[112:115], v[216:219], v[68:83]
	v_exp_f32_e32 v130, v50
	v_add_f32_e32 v233, v128, v129
	v_exp_f32_e32 v131, v51
	v_cvt_pk_bf16_f32 v198, v128, v129
	s_waitcnt lgkmcnt(1)
	v_mfma_f32_32x32x16_bf16 v[52:67], v[116:119], v[250:253], v[52:67]
	v_add_f32_e32 v254, v254, v233
	v_add_f32_e32 v224, v130, v131
	v_cvt_pk_bf16_f32 v199, v130, v131
	v_add_f32_e32 v254, v254, v224
	s_waitcnt lgkmcnt(0)
	v_mfma_f32_32x32x16_bf16 v[68:83], v[120:123], v[250:253], v[68:83]
	v_cmp_lt_f32_e32 vcc, 0x43800000, v254
	s_cbranch_vccnz .LpfU_s0

.LpfU_nr0:
	s_mov_b32 s5, 0
	v_exp_f32_e32 v124, v52
	v_exp_f32_e32 v125, v53
	v_exp_f32_e32 v126, v54
	v_add_f32_e32 v224, v124, v125
	s_waitcnt lgkmcnt(4)
	v_mfma_f32_32x32x16_bf16 v[4:19], v[164:167], v[184:187], v[4:19]
	v_exp_f32_e32 v127, v55
	v_cvt_pk_bf16_f32 v144, v124, v125
	v_mov_b32_e32 v254, v224
	v_exp_f32_e32 v128, v56
	s_waitcnt lgkmcnt(2)
	v_mfma_f32_32x32x16_bf16 v[20:35], v[168:171], v[184:187], v[20:35]
	ds_read_b64_tr_b16 v[176:177], v162 offset:42048
	ds_read_b64_tr_b16 v[178:179], v162 offset:43584
	v_add_f32_e32 v226, v126, v127
	v_exp_f32_e32 v129, v57
	v_cvt_pk_bf16_f32 v145, v126, v127
	v_add_f32_e32 v254, v254, v226
	s_waitcnt lgkmcnt(2)
	v_mfma_f32_32x32x16_bf16 v[4:19], v[172:175], v[188:191], v[4:19]
	ds_read_b64_tr_b16 v[164:165], v162 offset:45056
	ds_read_b64_tr_b16 v[166:167], v162 offset:46592
	v_exp_f32_e32 v130, v58
	v_add_f32_e32 v233, v128, v129
	v_exp_f32_e32 v131, v59
	v_cvt_pk_bf16_f32 v146, v128, v129
	s_waitcnt lgkmcnt(2)
	v_mfma_f32_32x32x16_bf16 v[20:35], v[176:179], v[188:191], v[20:35]
	ds_read_b64_tr_b16 v[168:169], v162 offset:45120
	ds_read_b64_tr_b16 v[170:171], v162 offset:46656
	v_add_f32_e32 v254, v254, v233
	v_exp_f32_e32 v124, v60
	v_add_f32_e32 v224, v130, v131
	v_exp_f32_e32 v125, v61
	s_waitcnt lgkmcnt(2)
	v_mfma_f32_32x32x16_bf16 v[4:19], v[164:167], v[192:195], v[4:19]
	ds_read_b64_tr_b16 v[172:173], v162 offset:48128
	ds_read_b64_tr_b16 v[174:175], v162 offset:49664
	v_cvt_pk_bf16_f32 v147, v130, v131
	v_add_f32_e32 v254, v254, v224
	v_exp_f32_e32 v126, v62
	v_add_f32_e32 v226, v124, v125
	s_waitcnt lgkmcnt(2)
	v_mfma_f32_32x32x16_bf16 v[20:35], v[168:171], v[192:195], v[20:35]
	ds_read_b64_tr_b16 v[176:177], v162 offset:48192
	ds_read_b64_tr_b16 v[178:179], v162 offset:49728
	v_exp_f32_e32 v127, v63
	v_cvt_pk_bf16_f32 v140, v124, v125
	v_add_f32_e32 v254, v254, v226
	v_exp_f32_e32 v128, v64
	s_waitcnt lgkmcnt(2)
	v_mfma_f32_32x32x16_bf16 v[4:19], v[172:175], v[196:199], v[4:19]
	ds_read_b128 v[180:183], v155 offset:13312
	ds_read_b128 v[112:115], v155 offset:19968
	v_add_f32_e32 v233, v126, v127
	v_exp_f32_e32 v129, v65
	v_cvt_pk_bf16_f32 v141, v126, v127
	v_add_f32_e32 v254, v254, v233
	s_waitcnt lgkmcnt(2)
	v_mfma_f32_32x32x16_bf16 v[20:35], v[176:179], v[196:199], v[20:35]
	s_barrier
	s_waitcnt vmcnt(0)
	ds_write_b128 v157, v[104:107]
	ds_write_b64 v158, v[108:109] offset:128
	ds_write_b128 v151, v[100:103] offset:26624
	s_add_i32 s2, s51, 2
	s_cmp_lt_i32 s2, s50
	s_cbranch_scc0 .LpfU_nl
	s_add_i32 s2, s52, 0x1000
	buffer_load_dwordx2 v[108:109], v161, s[12:15], s2 offen
	s_add_i32 s3, s53, 0xfe060000
	buffer_load_dwordx4 v[104:107], v150, s[12:15], s3 offen
	s_add_i32 s4, s53, 0x20000
	buffer_load_dwordx4 v[100:103], v150, s[12:15], s4 offen
.LpfU_nl:
	ds_read_b128 v[116:119], v155 offset:13344
	ds_read_b128 v[120:123], v155 offset:20000
	v_exp_f32_e32 v130, v66
	v_add_f32_e32 v224, v128, v129
	v_exp_f32_e32 v131, v67
	v_cvt_pk_bf16_f32 v142, v128, v129
	s_waitcnt lgkmcnt(6)
	v_mfma_f32_32x32x16_bf16 v[84:99], v[180:183], v[200:203], v[234:249]
	ds_read_b128 v[180:183], v155 offset:13376
	v_add_f32_e32 v254, v254, v224
	v_exp_f32_e32 v124, v68
	v_add_f32_e32 v226, v130, v131
	v_exp_f32_e32 v125, v69
	s_waitcnt lgkmcnt(6)
	v_mfma_f32_32x32x16_bf16 v[36:51], v[112:115], v[200:203], v[234:249]
	ds_read_b128 v[112:115], v155 offset:20032
	v_cvt_pk_bf16_f32 v143, v130, v131
	v_add_f32_e32 v254, v254, v226
	v_exp_f32_e32 v126, v70
	v_add_f32_e32 v233, v124, v125
	s_waitcnt lgkmcnt(3)
	v_mfma_f32_32x32x16_bf16 v[84:99], v[116:119], v[204:207], v[84:99]
	s_barrier
	ds_read_b128 v[116:119], v155 offset:13408
	v_exp_f32_e32 v127, v71
	v_cvt_pk_bf16_f32 v136, v124, v125
	v_add_f32_e32 v254, v254, v233
	v_exp_f32_e32 v128, v72
	s_waitcnt lgkmcnt(3)
	v_mfma_f32_32x32x16_bf16 v[36:51], v[120:123], v[204:207], v[36:51]
	ds_read_b128 v[120:123], v155 offset:20064
	v_add_f32_e32 v224, v126, v127
	v_exp_f32_e32 v129, v73
	v_cvt_pk_bf16_f32 v137, v126, v127
	v_add_f32_e32 v254, v254, v224
	s_waitcnt lgkmcnt(3)
	v_mfma_f32_32x32x16_bf16 v[84:99], v[180:183], v[208:211], v[84:99]
	ds_read_b128 v[180:183], v155 offset:13440
	v_exp_f32_e32 v130, v74
	v_add_f32_e32 v226, v128, v129
	v_exp_f32_e32 v131, v75
	v_cvt_pk_bf16_f32 v138, v128, v129
	s_waitcnt lgkmcnt(3)
	v_mfma_f32_32x32x16_bf16 v[36:51], v[112:115], v[208:211], v[36:51]
	ds_read_b128 v[112:115], v155 offset:20096
	v_add_f32_e32 v254, v254, v226
	v_exp_f32_e32 v124, v76
	v_add_f32_e32 v233, v130, v131
	v_exp_f32_e32 v125, v77
	s_waitcnt lgkmcnt(3)
	v_mfma_f32_32x32x16_bf16 v[84:99], v[116:119], v[212:215], v[84:99]
	ds_read_b128 v[116:119], v155 offset:13472
	v_cvt_pk_bf16_f32 v139, v130, v131
	v_add_f32_e32 v254, v254, v233
	v_exp_f32_e32 v126, v78
	v_add_f32_e32 v224, v124, v125
	s_waitcnt lgkmcnt(3)
	v_mfma_f32_32x32x16_bf16 v[36:51], v[120:123], v[212:215], v[36:51]
	ds_read_b128 v[120:123], v155 offset:20128
	v_exp_f32_e32 v127, v79
	v_cvt_pk_bf16_f32 v132, v124, v125
	v_add_f32_e32 v254, v254, v224
	v_exp_f32_e32 v128, v80
	s_waitcnt lgkmcnt(3)
	v_mfma_f32_32x32x16_bf16 v[84:99], v[180:183], v[216:219], v[84:99]
	v_add_f32_e32 v226, v126, v127
	v_exp_f32_e32 v129, v81
	v_cvt_pk_bf16_f32 v133, v126, v127
	v_add_f32_e32 v254, v254, v226
	s_waitcnt lgkmcnt(2)
	v_mfma_f32_32x32x16_bf16 v[36:51], v[112:115], v[216:219], v[36:51]
	v_exp_f32_e32 v130, v82
	v_add_f32_e32 v233, v128, v129
	v_exp_f32_e32 v131, v83
	v_cvt_pk_bf16_f32 v134, v128, v129
	s_waitcnt lgkmcnt(1)
	v_mfma_f32_32x32x16_bf16 v[84:99], v[116:119], v[250:253], v[84:99]
	v_add_f32_e32 v254, v254, v233
	v_add_f32_e32 v224, v130, v131
	v_cvt_pk_bf16_f32 v135, v130, v131
	v_add_f32_e32 v254, v254, v224
	s_waitcnt lgkmcnt(0)
	v_mfma_f32_32x32x16_bf16 v[36:51], v[120:123], v[250:253], v[36:51]
	v_cmp_lt_f32_e32 vcc, 0x43800000, v254
	s_cbranch_vccnz .LpfU_s1
